# queue claim issued early also for latent units: SWA/MLA one tile before the loop end, latent Hyena after the second order loop
# baseline (speedup 1.0000x reference)
.Lhy_lat0_done:
.LBB0_1266:
	s_waitcnt vmcnt(0)
	s_cmp_lg_u64 s[6:7], 0
	s_cbranch_scc1 .Lqe5
	s_mov_b64 s[98:99], exec
	s_mov_b64 exec, s[4:5]
	s_cbranch_execz .Lqp5
	v_readlane_b32 s12, v252, 23
	v_readlane_b32 s13, v252, 24
	s_nop 1
	v_mov_b64_e32 v[254:255], s[12:13]
	global_atomic_add v253, v[254:255], v177, off sc0

.Lqe5:
	s_xor_b64 s[12:13], s[6:7], -1
	s_and_b64 s[16:17], s[6:7], exec
	s_cselect_b32 s16, s82, 0xddf2000
	s_add_u32 s16, s8, s16
	s_addc_u32 s17, s9, 0
	v_cndmask_b32_e64 v30, v35, v34, s[6:7]
	s_and_b64 s[6:7], s[6:7], exec
	s_mov_b32 s6, 0x9380
	s_cselect_b32 s6, 0x4380, s6
	v_lshl_add_u64 v[32:33], v[20:21], 1, s[16:17]
	v_lshl_add_u32 v31, v20, 1, s6
	s_movk_i32 s6, 0x2000
	v_add_co_u32_e32 v42, vcc, s6, v32
	ds_read_b64 v[40:41], v31
	s_nop 0
	v_addc_co_u32_e32 v43, vcc, 0, v33, vcc
	v_mov_b32_e32 v49, v18
	s_waitcnt lgkmcnt(0)
	v_lshlrev_b32_e32 v47, 16, v41
	v_lshlrev_b32_e32 v46, 16, v40
	v_and_b32_e32 v41, 0xffff0000, v41
	v_and_b32_e32 v40, 0xffff0000, v40
	v_mov_b32_e32 v18, v17
	v_mov_b32_e32 v48, v16
	v_pk_fma_f32 v[16:17], v[30:31], v[40:41], v[18:19] op_sel_hi:[0,1,1]
	v_pk_fma_f32 v[46:47], v[30:31], v[46:47], v[48:49] op_sel_hi:[0,1,1]
	s_mov_b64 s[6:7], -1
	s_and_b64 vcc, exec, s[12:13]
	s_waitcnt vmcnt(0)
	v_lshlrev_b32_e32 v45, 16, v141
	v_lshlrev_b32_e32 v44, 16, v140
	v_and_b32_e32 v43, 0xffff0000, v141
	v_and_b32_e32 v42, 0xffff0000, v140
	v_pk_mul_f32 v[16:17], v[16:17], v[42:43]
	v_pk_mul_f32 v[44:45], v[46:47], v[44:45]
	v_and_b32_sdwa v31, v17, v177 dst_sel:DWORD dst_unused:UNUSED_PAD src0_sel:WORD_1 src1_sel:DWORD
	v_and_b32_sdwa v40, v16, v177 dst_sel:DWORD dst_unused:UNUSED_PAD src0_sel:WORD_1 src1_sel:DWORD
	v_and_b32_sdwa v18, v45, v177 dst_sel:DWORD dst_unused:UNUSED_PAD src0_sel:WORD_1 src1_sel:DWORD
	v_and_b32_sdwa v19, v44, v177 dst_sel:DWORD dst_unused:UNUSED_PAD src0_sel:WORD_1 src1_sel:DWORD
	v_add3_u32 v17, v17, v31, s60
	v_add3_u32 v16, v16, v40, s60
	v_add3_u32 v19, v44, v19, s60
	v_add3_u32 v18, v45, v18, s60
	v_and_b32_e32 v17, 0xffff0000, v17
	v_and_b32_e32 v16, 0xffff0000, v16
	v_or_b32_sdwa v17, v17, v18 dst_sel:DWORD dst_unused:UNUSED_PAD src0_sel:DWORD src1_sel:WORD_1
	v_or_b32_sdwa v16, v16, v19 dst_sel:DWORD dst_unused:UNUSED_PAD src0_sel:DWORD src1_sel:WORD_1
	s_cbranch_vccz .LBB0_1268
	flat_store_dwordx2 v[22:23], v[16:17]
	s_mov_b64 s[6:7], 0

.LBB0_1303:
	s_add_i32 s8, s33, 2
	s_cmp_lg_u32 s8, s44
	s_cbranch_scc1 .Lqe3
	s_mov_b64 s[98:99], exec
	s_mov_b64 exec, s[4:5]
	s_cbranch_execz .Lqp3
	v_readlane_b32 s8, v252, 23
	v_readlane_b32 s9, v252, 24
	s_nop 1
	v_mov_b64_e32 v[254:255], s[8:9]
	global_atomic_add v253, v[254:255], v177, off sc0
.Lqp3:
	s_mov_b64 exec, s[98:99]
	s_mov_b32 s32, 1
.Lqe3:
	s_add_i32 s6, s33, 2
	s_cmp_ge_i32 s6, s44
	s_cbranch_scc1 .LBB0_1308
	s_cmp_lt_i32 s6, s92
	s_cbranch_scc1 .LBB0_1306
	s_add_u32 s8, s97, s95
	s_addc_u32 s9, 0, s96
	s_mov_b64 s[6:7], 0x3680000
	s_mov_b64 s[10:11], 0x3580000
	s_branch .LBB0_1307

.Lqp4:
	s_mov_b64 exec, s[98:99]
	s_mov_b32 s32, 1
.Lqe4:
	s_add_i32 s6, s33, 2
	s_cmp_ge_i32 s6, s44
	s_cbranch_scc1 .Lnm0_b1308
	s_cmp_lt_i32 s6, s92
	s_cbranch_scc1 .Lnm0_b1306
	s_add_u32 s8, s97, s95
	s_addc_u32 s9, 0, s96
	s_mov_b64 s[6:7], 0x3680000
	s_mov_b64 s[10:11], 0x3580000
	s_branch .Lnm0_b1307

.Lhy_lat1_done:
.LBB0_3023:
	s_waitcnt vmcnt(0)
	s_cmp_lg_u64 s[6:7], 0
	s_cbranch_scc1 .Lqe11
	s_mov_b64 s[98:99], exec
	s_mov_b64 exec, s[4:5]
	s_cbranch_execz .Lqp11
	v_readlane_b32 s12, v252, 23
	v_readlane_b32 s13, v252, 24
	s_nop 1
	v_mov_b64_e32 v[254:255], s[12:13]
	global_atomic_add v253, v[254:255], v176, off sc0

.Lqe11:
	s_xor_b64 s[12:13], s[6:7], -1
	s_and_b64 s[18:19], s[6:7], exec
	s_cselect_b32 s18, s2, 0xddf2000
	s_add_u32 s18, s8, s18
	s_addc_u32 s19, s9, 0
	v_cndmask_b32_e64 v30, v35, v34, s[6:7]
	s_and_b64 s[6:7], s[6:7], exec
	s_mov_b32 s6, 0x9380
	s_cselect_b32 s6, 0x4380, s6
	v_lshl_add_u64 v[32:33], v[20:21], 1, s[18:19]
	v_lshl_add_u32 v31, v20, 1, s6
	s_movk_i32 s6, 0x2000
	v_add_co_u32_e32 v42, vcc, s6, v32
	ds_read_b64 v[40:41], v31
	s_nop 0
	v_addc_co_u32_e32 v43, vcc, 0, v33, vcc
	v_mov_b32_e32 v49, v18
	s_waitcnt lgkmcnt(0)
	v_lshlrev_b32_e32 v47, 16, v41
	v_lshlrev_b32_e32 v46, 16, v40
	v_and_b32_e32 v41, 0xffff0000, v41
	v_and_b32_e32 v40, 0xffff0000, v40
	v_mov_b32_e32 v18, v17
	v_mov_b32_e32 v48, v16
	v_pk_fma_f32 v[16:17], v[30:31], v[40:41], v[18:19] op_sel_hi:[0,1,1]
	v_pk_fma_f32 v[46:47], v[30:31], v[46:47], v[48:49] op_sel_hi:[0,1,1]
	s_mov_b64 s[6:7], -1
	s_and_b64 vcc, exec, s[12:13]
	s_waitcnt vmcnt(0)
	v_lshlrev_b32_e32 v45, 16, v141
	v_lshlrev_b32_e32 v44, 16, v140
	v_and_b32_e32 v43, 0xffff0000, v141
	v_and_b32_e32 v42, 0xffff0000, v140
	v_pk_mul_f32 v[16:17], v[16:17], v[42:43]
	v_pk_mul_f32 v[44:45], v[46:47], v[44:45]
	v_and_b32_sdwa v31, v17, v176 dst_sel:DWORD dst_unused:UNUSED_PAD src0_sel:WORD_1 src1_sel:DWORD
	v_and_b32_sdwa v40, v16, v176 dst_sel:DWORD dst_unused:UNUSED_PAD src0_sel:WORD_1 src1_sel:DWORD
	v_and_b32_sdwa v18, v45, v176 dst_sel:DWORD dst_unused:UNUSED_PAD src0_sel:WORD_1 src1_sel:DWORD
	v_and_b32_sdwa v19, v44, v176 dst_sel:DWORD dst_unused:UNUSED_PAD src0_sel:WORD_1 src1_sel:DWORD
	v_add3_u32 v17, v17, v31, s93
	v_add3_u32 v16, v16, v40, s93
	v_add3_u32 v19, v44, v19, s93
	v_add3_u32 v18, v45, v18, s93
	v_and_b32_e32 v17, 0xffff0000, v17
	v_and_b32_e32 v16, 0xffff0000, v16
	v_or_b32_sdwa v17, v17, v18 dst_sel:DWORD dst_unused:UNUSED_PAD src0_sel:DWORD src1_sel:WORD_1
	v_or_b32_sdwa v16, v16, v19 dst_sel:DWORD dst_unused:UNUSED_PAD src0_sel:DWORD src1_sel:WORD_1
	s_cbranch_vccz .LBB0_3025
	flat_store_dwordx2 v[22:23], v[16:17]
	s_mov_b64 s[6:7], 0

.LBB0_3060:
	s_add_i32 s8, s82, 2
	s_cmp_lg_u32 s8, s44
	s_cbranch_scc1 .Lqe9
	s_mov_b64 s[98:99], exec
	s_mov_b64 exec, s[4:5]
	s_cbranch_execz .Lqp9
	v_readlane_b32 s8, v252, 23
	v_readlane_b32 s9, v252, 24
	s_nop 1
	v_mov_b64_e32 v[254:255], s[8:9]
	global_atomic_add v253, v[254:255], v176, off sc0
.Lqp9:
	s_mov_b64 exec, s[98:99]
	s_mov_b32 s32, 1
.Lqe9:
	s_add_i32 s6, s82, 2
	s_cmp_ge_i32 s6, s44
	s_cbranch_scc1 .LBB0_3065
	s_cmp_lt_i32 s6, s76
	s_cbranch_scc1 .LBB0_3063
	s_add_u32 s8, s81, s79
	s_addc_u32 s9, 0, s80
	s_mov_b64 s[6:7], 0x3680000
	s_mov_b64 s[10:11], 0x3580000
	s_branch .LBB0_3064

.Lqp10:
	s_mov_b64 exec, s[98:99]
	s_mov_b32 s32, 1
.Lqe10:
	s_add_i32 s6, s82, 2
	s_cmp_ge_i32 s6, s44
	s_cbranch_scc1 .Lnm1_b3065
	s_cmp_lt_i32 s6, s76
	s_cbranch_scc1 .Lnm1_b3063
	s_add_u32 s8, s81, s79
	s_addc_u32 s9, 0, s80
	s_mov_b64 s[6:7], 0x3680000
	s_mov_b64 s[10:11], 0x3580000
	s_branch .Lnm1_b3064
